# EpiNorm step 4: one 16-byte sc1 load of the four partial sums instead of four dependent loads
# speedup vs baseline: 1.0515x; 1.0022x over previous
.LBB0_734:
.LBB0_735:
	s_waitcnt vmcnt(0) lgkmcnt(0)
	s_barrier
	s_and_saveexec_b64 s[8:9], s[38:39]
	s_cbranch_execz .LBB0_737
	v_lshl_add_u64 v[128:129], v[128:129], 4, s[14:15]
	global_load_dwordx4 v[248:251], v[128:129], off sc1
	s_waitcnt vmcnt(0)
	v_add_f32_e32 v131, 0, v248
	v_add_f32_e32 v131, v131, v249
	v_add_f32_e32 v131, v131, v250
	v_add_f32_e32 v128, v131, v251
	v_fmamk_f32 v128, v128, 0x3a800000, v224
	v_cmp_gt_f32_e32 vcc, s85, v128
	v_mul_f32_e32 v129, 0x4b800000, v128
	s_nop 0
	v_cndmask_b32_e32 v128, v128, v129, vcc
	v_rsq_f32_e32 v128, v128
	s_nop 0
	v_mul_f32_e32 v129, 0x45800000, v128
	v_cndmask_b32_e32 v128, v128, v129, vcc
	v_lshl_add_u32 v129, v130, 2, 0
	ds_write_b32 v129, v128 offset:8192

.LBB0_1012:
.LBB0_1013:
	s_waitcnt vmcnt(0) lgkmcnt(0)
	s_barrier
	s_and_saveexec_b64 s[8:9], s[38:39]
	s_cbranch_execz .LBB0_1015
	v_lshl_add_u64 v[0:1], v[0:1], 4, s[6:7]
	global_load_dwordx4 v[248:251], v[0:1], off sc1
	s_waitcnt vmcnt(0)
	v_add_f32_e32 v3, 0, v248
	v_add_f32_e32 v3, v3, v249
	v_add_f32_e32 v3, v3, v250
	v_add_f32_e32 v0, v3, v251
	v_fmamk_f32 v0, v0, 0x3a800000, v224
	v_cmp_gt_f32_e32 vcc, s85, v0
	v_mul_f32_e32 v1, 0x4b800000, v0
	s_nop 0
	v_cndmask_b32_e32 v0, v0, v1, vcc
	v_rsq_f32_e32 v0, v0
	s_nop 0
	v_mul_f32_e32 v1, 0x45800000, v0
	v_cndmask_b32_e32 v0, v0, v1, vcc
	v_lshl_add_u32 v1, v2, 2, 0
	ds_write_b32 v1, v0 offset:8192

.LBB0_1067:
.LBB0_1068:
	s_waitcnt vmcnt(0) lgkmcnt(0)
	s_barrier
	s_and_saveexec_b64 s[6:7], s[38:39]
	s_cbranch_execz .LBB0_1070
	v_lshl_add_u64 v[128:129], v[128:129], 4, s[12:13]
	global_load_dwordx4 v[248:251], v[128:129], off sc1
	s_waitcnt vmcnt(0)
	v_add_f32_e32 v131, 0, v248
	v_add_f32_e32 v131, v131, v249
	v_add_f32_e32 v131, v131, v250
	v_add_f32_e32 v128, v131, v251
	v_fmamk_f32 v128, v128, 0x3a800000, v224
	v_cmp_gt_f32_e32 vcc, s85, v128
	v_mul_f32_e32 v129, 0x4b800000, v128
	s_nop 0
	v_cndmask_b32_e32 v128, v128, v129, vcc
	v_rsq_f32_e32 v128, v128
	s_nop 0
	v_mul_f32_e32 v129, 0x45800000, v128
	v_cndmask_b32_e32 v128, v128, v129, vcc
	v_lshl_add_u32 v129, v130, 2, 0
	ds_write_b32 v129, v128 offset:8192
